# FFN2-up epilogue: row sum-of-squares prefetched at unit start (2 packed loads + ds_bpermute) instead of 8 dependent loads + vmcnt(0) after the last MFMA
# baseline (speedup 1.0000x reference)
;     __device__ bool next(int i, Unit& u) const {
;         const long L = (long)i * G + c; if (L >= nwg) return false;
;         int wgid = (int)L; { const int q = nwg / NXCD, r = nwg % NXCD, xcd = wgid % NXCD, off = wgid / NXCD; wgid = (xcd < r ? xcd * (q + 1) : r * (q + 1) + (xcd - r) * q) + off; }
;         const int nig = wgm * nN, gid = wgid / nig, fm = gid * wgm, gsz = (nM - fm) < wgm ? (nM - fm) : wgm;
;         u.pm = fm + ((wgid % nig) % gsz); u.pn = (wgid % nig) / gsz; u.pb = bdiv ? (u.pm / bdiv) : u.pn; return true;
;     __device__ __forceinline__ void operator()(const Acc& acc, const Unit& u, int wr, int wc, int fr, int fq) const {
;     ...
;                     for (int m = 0; m < 4; ++m) t[ai][m] = ss[(size_t)u.pm * BM + ai * HALF + wr * 64 + m * 16 + fr];
.LBB0_1127:
	s_mov_b32 s98, s24
	s_ashr_i32 s99, s24, 31
	s_lshl_b64 s[98:99], s[98:99], 10
	v_lshrrev_b32_e32 v252, 4, v228
	v_lshlrev_b32_e32 v252, 6, v252
	v_mov_b32_e32 v253, 0
	v_lshl_add_u64 v[254:255], v[136:137], 0, s[98:99]
	v_lshl_add_u64 v[254:255], v[254:255], 0, v[252:253]
	global_load_dword v252, v[254:255], off
	global_load_dword v253, v[254:255], off offset:512
	s_add_i32 s61, s61, 1
	s_mul_i32 s8, s61, s59
	s_mul_hi_u32 s9, s61, s60
	s_add_i32 s9, s9, s8
	s_mul_i32 s8, s61, s60
	s_add_u32 s14, s8, s2
	s_addc_u32 s15, s9, s3
	v_cmp_gt_i64_e32 vcc, s[14:15], v[146:147]
	v_cmp_lt_i64_e64 s[8:9], s[14:15], v[144:145]
	s_cbranch_vccnz .LBB0_1129
	s_ashr_i32 s15, s14, 31
	s_lshr_b32 s15, s15, 29
	s_add_i32 s15, s14, s15
	s_ashr_i32 s16, s15, 3
	s_and_b32 s15, s15, -8
	s_sub_i32 s14, s14, s15
	s_cmp_lt_i32 s14, 0
	s_cselect_b32 s15, s39, 0x2b0
	s_mul_i32 s14, s14, s15
	s_add_i32 s14, s14, s16
	s_mul_hi_i32 s15, s14, 0x2fa0be83
	s_lshr_b32 s16, s15, 31
	s_ashr_i32 s15, s15, 5
	s_add_i32 s15, s15, s16
	s_lshl_b32 s16, s15, 2
	s_sub_i32 s17, 0x80, s16
	s_min_i32 s17, s17, 4
	s_abs_i32 s18, s17
	v_cvt_f32_u32_e32 v0, s18
	s_sub_i32 s20, 0, s18
	s_mulk_i32 s15, 0xac
	s_sub_i32 s14, s14, s15
	v_rcp_iflag_f32_e32 v0, v0
	s_abs_i32 s15, s14
	s_xor_b32 s19, s14, s17
	s_ashr_i32 s19, s19, 31
	v_mul_f32_e32 v0, 0x4f7ffffe, v0
	v_cvt_u32_f32_e32 v0, v0
	s_nop 0
	v_readfirstlane_b32 s21, v0
	s_mul_i32 s20, s20, s21
	s_mul_hi_u32 s20, s21, s20
	s_add_i32 s21, s21, s20
	s_mul_hi_u32 s20, s15, s21
	s_mul_i32 s21, s20, s18
	s_sub_i32 s15, s15, s21
	s_add_i32 s22, s20, 1
	s_sub_i32 s21, s15, s18
	s_cmp_ge_u32 s15, s18
	s_cselect_b32 s20, s22, s20
	s_cselect_b32 s15, s21, s15
	s_add_i32 s21, s20, 1
	s_cmp_ge_u32 s15, s18
	s_cselect_b32 s15, s21, s20
	s_xor_b32 s15, s15, s19
	s_sub_i32 s40, s15, s19
	s_mul_i32 s15, s40, s17
	s_sub_i32 s14, s14, s15
	s_add_i32 s42, s16, s14

;     __device__ __forceinline__ void operator()(const Acc& acc, const Unit& u, int wr, int wc, int fr, int fq) const {
;     ...
;             if (u.pm != last_pm) {
;                 float t[2][4];
; #pragma unroll
;                 for (int ai = 0; ai < 2; ++ai)
; #pragma unroll
;                     for (int m = 0; m < 4; ++m) t[ai][m] = ss[(size_t)u.pm * BM + ai * HALF + wr * 64 + m * 16 + fr];
; #pragma unroll
;                 for (int ai = 0; ai < 2; ++ai)
; #pragma unroll
;                     for (int m = 0; m < 4; ++m) { const float rs = rsqrtf(t[ai][m] * (1.f / DM) + EPS); c0[ai][m] = -1.4426950408889634f * rs; c1[ai][m] = rs * rs; }
;                 last_pm = u.pm;
;             }
.LBB0_1134:
	s_cmp_lg_u32 s24, s48
	s_mov_b64 s[50:51], -1
	s_cbranch_scc0 .LBB0_1136
	s_ashr_i32 s25, s24, 31
	s_lshl_b64 s[10:11], s[24:25], 10
	v_and_b32_e32 v164, 15, v228
	v_lshlrev_b32_e32 v164, 2, v164
	v_add_u32_e32 v165, 64, v164
	v_add_u32_e32 v174, 0x80, v164
	v_add_u32_e32 v175, 0xc0, v164
	ds_bpermute_b32 v166, v164, v252
	ds_bpermute_b32 v167, v165, v252
	ds_bpermute_b32 v168, v174, v252
	ds_bpermute_b32 v169, v175, v252
	ds_bpermute_b32 v170, v164, v253
	ds_bpermute_b32 v171, v165, v253
	ds_bpermute_b32 v172, v174, v253
	ds_bpermute_b32 v173, v175, v253
	s_waitcnt lgkmcnt(0)
	v_mov_b64_e32 v[164:165], s[34:35]
	v_pk_fma_f32 v[166:167], v[166:167], s[30:31], v[164:165] op_sel_hi:[1,0,0]
	s_nop 0
	v_cmp_gt_f32_e32 vcc, s64, v166
	v_pk_fma_f32 v[168:169], v[168:169], s[30:31], v[164:165] op_sel_hi:[1,0,0]
	v_cmp_gt_f32_e64 s[10:11], s64, v167
	v_pk_fma_f32 v[170:171], v[170:171], s[30:31], v[164:165] op_sel_hi:[1,0,0]
	v_mul_f32_e32 v174, 0x4b800000, v168
	v_pk_fma_f32 v[164:165], v[172:173], s[30:31], v[164:165] op_sel_hi:[1,0,0]
	v_mul_f32_e32 v172, 0x4b800000, v166
	v_mul_f32_e32 v173, 0x4b800000, v167
	v_mul_f32_e32 v175, 0x4b800000, v169
	v_mul_f32_e32 v176, 0x4b800000, v170
	v_mul_f32_e32 v177, 0x4b800000, v171
	v_mul_f32_e32 v178, 0x4b800000, v164
	v_mul_f32_e32 v179, 0x4b800000, v165
	v_cmp_gt_f32_e64 s[12:13], s64, v168
	v_cmp_gt_f32_e64 s[14:15], s64, v169
	v_cmp_gt_f32_e64 s[16:17], s64, v170
	v_cmp_gt_f32_e64 s[18:19], s64, v171
	v_cmp_gt_f32_e64 s[20:21], s64, v164
	v_cmp_gt_f32_e64 s[22:23], s64, v165
	v_cndmask_b32_e32 v166, v166, v172, vcc
	v_cndmask_b32_e64 v167, v167, v173, s[10:11]
	v_cndmask_b32_e64 v168, v168, v174, s[12:13]
	v_cndmask_b32_e64 v169, v169, v175, s[14:15]
	v_cndmask_b32_e64 v170, v170, v176, s[16:17]
	v_cndmask_b32_e64 v171, v171, v177, s[18:19]
	v_cndmask_b32_e64 v172, v164, v178, s[20:21]
	v_cndmask_b32_e64 v173, v165, v179, s[22:23]
	v_rsq_f32_e32 v164, v166
	v_rsq_f32_e32 v165, v167
	v_rsq_f32_e32 v166, v168
	v_rsq_f32_e32 v167, v169
	v_rsq_f32_e32 v168, v170
	v_rsq_f32_e32 v169, v171
	v_rsq_f32_e32 v170, v172
	v_rsq_f32_e32 v171, v173
	v_pk_mul_f32 v[172:173], v[164:165], s[36:37] op_sel_hi:[1,0]
	v_pk_mul_f32 v[174:175], v[166:167], s[36:37] op_sel_hi:[1,0]
	v_pk_mul_f32 v[176:177], v[168:169], s[36:37] op_sel_hi:[1,0]
	v_pk_mul_f32 v[178:179], v[170:171], s[36:37] op_sel_hi:[1,0]
	v_cndmask_b32_e64 v173, v165, v173, s[10:11]
	v_cndmask_b32_e32 v172, v164, v172, vcc
	v_cndmask_b32_e64 v187, v167, v175, s[14:15]
	v_cndmask_b32_e64 v186, v166, v174, s[12:13]
	v_cndmask_b32_e64 v189, v169, v177, s[18:19]
	v_cndmask_b32_e64 v188, v168, v176, s[16:17]
	v_cndmask_b32_e64 v191, v171, v179, s[22:23]
	v_cndmask_b32_e64 v190, v170, v178, s[20:21]
	v_pk_mul_f32 v[164:165], v[172:173], s[38:39] op_sel_hi:[1,0]
	v_pk_mul_f32 v[166:167], v[172:173], v[172:173]
	v_pk_mul_f32 v[174:175], v[186:187], s[38:39] op_sel_hi:[1,0]
	v_pk_mul_f32 v[168:169], v[186:187], v[186:187]
	v_pk_mul_f32 v[176:177], v[188:189], s[38:39] op_sel_hi:[1,0]
	v_pk_mul_f32 v[170:171], v[188:189], v[188:189]
	v_pk_mul_f32 v[178:179], v[190:191], s[38:39] op_sel_hi:[1,0]
	v_pk_mul_f32 v[172:173], v[190:191], v[190:191]
	s_mov_b64 s[10:11], s[24:25]
	s_cbranch_execz .LBB0_1137
	s_branch .LBB0_1138

; __global__ void __launch_bounds__(512, 2) fwd_mega(Args a) {
	.amdhsa_kernel _Z8fwd_mega4Args
		.amdhsa_group_segment_fixed_size 0
		.amdhsa_private_segment_fixed_size 0
		.amdhsa_kernarg_size 504
		.amdhsa_user_sgpr_count 2
		.amdhsa_user_sgpr_dispatch_ptr 0
		.amdhsa_user_sgpr_queue_ptr 0
		.amdhsa_user_sgpr_kernarg_segment_ptr 1
		.amdhsa_user_sgpr_dispatch_id 0
		.amdhsa_user_sgpr_kernarg_preload_length 0
		.amdhsa_user_sgpr_kernarg_preload_offset 0
		.amdhsa_user_sgpr_private_segment_size 0
		.amdhsa_uses_dynamic_stack 0
		.amdhsa_enable_private_segment 0
		.amdhsa_system_sgpr_workgroup_id_x 1
		.amdhsa_system_sgpr_workgroup_id_y 0
		.amdhsa_system_sgpr_workgroup_id_z 0
		.amdhsa_system_sgpr_workgroup_info 0
		.amdhsa_system_vgpr_workitem_id 2
		.amdhsa_next_free_vgpr 256
		.amdhsa_next_free_sgpr 102
		.amdhsa_accum_offset 256
		.amdhsa_reserve_vcc 1
		.amdhsa_float_round_mode_32 0
		.amdhsa_float_round_mode_16_64 0
		.amdhsa_float_denorm_mode_32 3
		.amdhsa_float_denorm_mode_16_64 3
		.amdhsa_dx10_clamp 1
		.amdhsa_ieee_mode 1
		.amdhsa_fp16_overflow 0
		.amdhsa_tg_split 0
		.amdhsa_exception_fp_ieee_invalid_op 0
		.amdhsa_exception_fp_denorm_src 0
		.amdhsa_exception_fp_ieee_div_zero 0
		.amdhsa_exception_fp_ieee_overflow 0
		.amdhsa_exception_fp_ieee_underflow 0
		.amdhsa_exception_fp_ieee_inexact 0
		.amdhsa_exception_int_div_zero 0
	.end_amdhsa_kernel

; __global__ void __launch_bounds__(512, 2) fwd_mega(Args a) {
amdhsa.kernels:
  - .agpr_count:     0
    .args:
      - .offset:         0
        .size:           248
        .value_kind:     by_value
      - .offset:         248
        .size:           4
        .value_kind:     hidden_block_count_x
      - .offset:         252
        .size:           4
        .value_kind:     hidden_block_count_y
      - .offset:         256
        .size:           4
        .value_kind:     hidden_block_count_z
      - .offset:         260
        .size:           2
        .value_kind:     hidden_group_size_x
      - .offset:         262
        .size:           2
        .value_kind:     hidden_group_size_y
      - .offset:         264
        .size:           2
        .value_kind:     hidden_group_size_z
      - .offset:         266
        .size:           2
        .value_kind:     hidden_remainder_x
      - .offset:         268
        .size:           2
        .value_kind:     hidden_remainder_y
      - .offset:         270
        .size:           2
        .value_kind:     hidden_remainder_z
      - .offset:         288
        .size:           8
        .value_kind:     hidden_global_offset_x
      - .offset:         296
        .size:           8
        .value_kind:     hidden_global_offset_y
      - .offset:         304
        .size:           8
        .value_kind:     hidden_global_offset_z
      - .offset:         312
        .size:           2
        .value_kind:     hidden_grid_dims
      - .offset:         336
        .size:           8
        .value_kind:     hidden_multigrid_sync_arg
      - .offset:         368
        .size:           4
        .value_kind:     hidden_dynamic_lds_size
    .group_segment_fixed_size: 0
    .kernarg_segment_align: 8
    .kernarg_segment_size: 504
    .language:       OpenCL C
    .language_version:
      - 2
      - 0
    .max_flat_workgroup_size: 512
    .name:           _Z8fwd_mega4Args
    .private_segment_fixed_size: 0
    .sgpr_count:     108
    .sgpr_spill_count: 73
    .symbol:         _Z8fwd_mega4Args.kd
    .uniform_work_group_size: 1
    .uses_dynamic_stack: false
    .vgpr_count:     256
    .vgpr_spill_count: 0
    .wavefront_size: 64
